# P0 rmsnorm: wave-wide row sum by DPP adds (quad_perm, row_half_mirror, row_mirror) and permlane16/32 swaps instead of six serialised ds_bpermute round trips
# baseline (speedup 1.0000x reference)
; DI u32x2 pk4(f32x4 v) { u32x2 r; r.x = pk2(v[0], v[1]); r.y = pk2(v[2], v[3]); return r; }
; DI float wave_sum(float v) {
; #pragma unroll
;     for (int o = 1; o < 64; o <<= 1) v += __shfl_xor(v, o);
;     return v;
; DI void prologue(KArgs ap, int gw, int NGW, int lane) {
;     ...
;             f32x4 v[4]; float s = 0.f;
; #pragma unroll
;             for (int j = 0; j < 4; ++j) { v[j] = xr[64 * j]; s += (v[j][0] * v[j][0] + v[j][1] * v[j][1]) + (v[j][2] * v[j][2] + v[j][3] * v[j][3]); }
;             const float rstd = rsqrtf(wave_sum(s) * (1.f / DM) + EPS);
;             u32x2* o8 = (u32x2*)(XN + (size_t)m * DM) + lane;
; #pragma unroll
;             for (int j = 0; j < 4; ++j) o8[64 * j] = pk4(v[j] * rstd * gg[j]);
.Lxn_nold:
	v_pk_mul_f32 v[42:43], v[28:29], v[28:29]
	v_pk_mul_f32 v[44:45], v[26:27], v[26:27]
	v_pk_mul_f32 v[46:47], v[32:33], v[32:33]
	v_pk_mul_f32 v[48:49], v[30:31], v[30:31]
	v_pk_mov_b32 v[54:55], v[44:45], v[42:43] op_sel:[1,0]
	v_mov_b32_e32 v45, v43
	v_pk_mov_b32 v[42:43], v[48:49], v[46:47] op_sel:[1,0]
	v_mov_b32_e32 v49, v47
	v_mul_f32_e32 v53, v34, v34
	v_mul_f32_e32 v50, v39, v39
	v_mul_f32_e32 v52, v41, v41
	v_pk_add_f32 v[44:45], v[54:55], v[44:45]
	v_pk_add_f32 v[42:43], v[42:43], v[48:49]
	v_mul_f32_e32 v56, v35, v35
	v_mul_f32_e32 v57, v36, v36
	v_mul_f32_e32 v58, v37, v37
	v_pk_fma_f32 v[46:47], v[38:39], v[38:39], v[50:51] op_sel_hi:[1,1,0]
	v_pk_fma_f32 v[50:51], v[40:41], v[40:41], v[52:53] op_sel_hi:[1,1,0]
	v_pk_add_f32 v[44:45], v[44:45], v[44:45] op_sel:[0,1] op_sel_hi:[1,0]
	v_pk_add_f32 v[42:43], v[42:43], v[42:43] op_sel:[0,1] op_sel_hi:[1,0]
	v_mov_b32_e32 v47, v57
	v_mov_b32_e32 v51, v58
	v_mov_b32_e32 v45, v53
	v_mov_b32_e32 v43, v56
	v_pk_add_f32 v[46:47], v[46:47], v[50:51]
	v_pk_add_f32 v[42:43], v[44:45], v[42:43]
	s_nop 0
	v_pk_add_f32 v[42:43], v[42:43], v[46:47]
	s_nop 0
	v_add_f32_e32 v42, v42, v43
	s_nop 1
	v_add_f32_dpp v42, v42, v42 quad_perm:[1,0,3,2] row_mask:0xf bank_mask:0xf
	s_nop 1
	v_add_f32_dpp v42, v42, v42 quad_perm:[2,3,0,1] row_mask:0xf bank_mask:0xf
	s_nop 1
	v_add_f32_dpp v42, v42, v42 row_half_mirror row_mask:0xf bank_mask:0xf
	s_nop 1
	v_add_f32_dpp v42, v42, v42 row_mirror row_mask:0xf bank_mask:0xf
	v_mov_b32_e32 v43, v42
	s_nop 1
	v_permlane16_swap_b32_e32 v43, v42
	v_add_f32_e32 v42, v42, v43
	v_mov_b32_e32 v43, v42
	s_nop 1
	v_permlane32_swap_b32_e32 v43, v42
	v_add_f32_e32 v44, v42, v43
	v_lshl_add_u64 v[42:43], v[16:17], 0, s[98:99]
	v_fmamk_f32 v44, v44, 0x3a800000, v25
	v_mul_f32_e32 v45, 0x4b800000, v44
	v_cmp_gt_f32_e32 vcc, s20, v44
	s_nop 1
	v_cndmask_b32_e32 v44, v44, v45, vcc
	v_rsq_f32_e32 v44, v44
	s_nop 0
	v_mul_f32_e32 v45, 0x45800000, v44
	v_cndmask_b32_e32 v44, v44, v45, vcc
	v_pk_mul_f32 v[26:27], v[26:27], v[44:45] op_sel_hi:[1,0]
	v_pk_mul_f32 v[28:29], v[28:29], v[44:45] op_sel_hi:[1,0]
	v_pk_mul_f32 v[30:31], v[30:31], v[44:45] op_sel_hi:[1,0]
	v_pk_mul_f32 v[32:33], v[32:33], v[44:45] op_sel_hi:[1,0]
	v_pk_mul_f32 v[38:39], v[38:39], v[44:45] op_sel_hi:[1,0]
	v_pk_mul_f32 v[40:41], v[40:41], v[44:45] op_sel_hi:[1,0]
	v_pk_mul_f32 v[34:35], v[34:35], v[44:45] op_sel_hi:[1,0]
	v_pk_mul_f32 v[36:37], v[36:37], v[44:45] op_sel_hi:[1,0]
	v_pk_mul_f32 v[28:29], v[2:3], v[28:29]
	v_pk_mul_f32 v[26:27], v[0:1], v[26:27]
	v_pk_mul_f32 v[32:33], v[6:7], v[32:33]
	v_pk_mul_f32 v[30:31], v[4:5], v[30:31]
	v_pk_mul_f32 v[40:41], v[10:11], v[40:41]
	v_pk_mul_f32 v[38:39], v[8:9], v[38:39]
	v_pk_mul_f32 v[36:37], v[14:15], v[36:37]
	v_pk_mul_f32 v[34:35], v[12:13], v[34:35]
	v_cvt_pk_bf16_f32 v26, v26, v27
	v_cvt_pk_bf16_f32 v27, v28, v29
	v_cvt_pk_bf16_f32 v28, v30, v31
	v_cvt_pk_bf16_f32 v29, v32, v33
	v_cvt_pk_bf16_f32 v30, v38, v39
	v_cvt_pk_bf16_f32 v31, v40, v41
	v_cvt_pk_bf16_f32 v32, v34, v35
	v_cvt_pk_bf16_f32 v33, v36, v37
	global_store_dwordx2 v[42:43], v[26:27], off
	global_store_dwordx2 v[42:43], v[28:29], off offset:512
	global_store_dwordx2 v[42:43], v[30:31], off offset:1024
	global_store_dwordx2 v[42:43], v[32:33], off offset:1536
	s_cmp_lg_u32 s32, 0
	s_cbranch_scc1 .Lxn_top
	s_branch .Lbt_fill
	s_branch .Lbt_fill
